# v38 plus K fragment reads: four up front, the other four one per QK MFMA
# baseline (speedup 1.0000x reference)
; #define LAS __attribute__((address_space(3)))
; #define ATT_SB __builtin_amdgcn_sched_barrier(0)
; template <bool NOSHIFT> __device__ __forceinline__ void diff_attn_unit(LAS unsigned char* lds, bf16_t* proj, const bf16_t* VT, int b, int h, int qb, const AttnConsts ac, const float* gsub, const int tid, bf16_t* obuf, int opitch, int ocol) {
;     ...
;         if (t + 2 < NT) ATT_ISSUE(t + 2);
;         const int kv0 = 64 * t;
;         if (c == 1 && t >= 1 && kv0 - 64 <= qmax) ATT_PV(sl_prev);
;         if (kv0 <= qmax) {
;             f32x16 p[2];
;             bf16x8 kf[2][4];
; #pragma unroll
;             for (int mt = 0; mt < 2; ++mt)
; #pragma unroll
;                 for (int ks = 0; ks < 4; ++ks) kf[mt][ks] = *(const LAS bf16x8*)(lds + bo + koff[mt][ks]);
;             if constexpr (!NOSHIFT) {
; #pragma unroll
;                 for (int mt = 0; mt < 2; ++mt)
; #pragma unroll
;                     for (int r = 0; r < 16; ++r) p[mt][r] = -ac.Mfix;
;             }
;             ATT_SB;
;             __builtin_amdgcn_s_setprio(1);
; #pragma unroll
;             for (int ks = 0; ks < 4; ++ks)
; #pragma unroll
;                 for (int mt = 0; mt < 2; ++mt) {
;                     if (NOSHIFT && ks == 0) { const f32x16 z = {0.f, 0.f, 0.f, 0.f, 0.f, 0.f, 0.f, 0.f, 0.f, 0.f, 0.f, 0.f, 0.f, 0.f, 0.f, 0.f}; p[mt] = __builtin_amdgcn_mfma_f32_32x32x16_bf16(kf[mt][ks], qf[ks], z, 0, 0, 0); }
;                     else p[mt] = __builtin_amdgcn_mfma_f32_32x32x16_bf16(kf[mt][ks], qf[ks], p[mt], 0, 0, 0);
;                 }
;             __builtin_amdgcn_s_setprio(0);
;             ATT_SB;
;             const bool diag = (t >= 2 * qb);
;             if (diag) {
;                 const int qrel = qrow - kv0 - 8 * hi;
; #pragma unroll
;                 for (int mt = 0; mt < 2; ++mt)
; #pragma unroll
;                     for (int r = 0; r < 16; ++r) { float v = __builtin_amdgcn_exp2f(p[mt][r]); if (32 * mt + 16 * (r >> 3) + (r & 7) > qrel) v = 0.f; p[mt][r] = v; l += v; }
;             } else {
; #pragma unroll
;                 for (int mt = 0; mt < 2; ++mt)
; #pragma unroll
;                     for (int r = 0; r < 16; ++r) { const float v = __builtin_amdgcn_exp2f(p[mt][r]); p[mt][r] = v; l += v; }
;             }
;             asm volatile("" ::: "memory");
; #pragma unroll
;             for (int kk = 0; kk < 4; ++kk) { const int mt = kk >> 1, r0 = 8 * (kk & 1); u32x4 w;
.Lfp_go:
	s_addk_i32 s14, 0x4000
	s_and_b32 s15, s14, 0xc000
	v_add_u32_e32 v7, s15, v179
	v_add_u32_e32 v96, s15, v183
	v_add_u32_e32 v240, s15, v186
	v_add_u32_e32 v241, s15, v187
	ds_read_b128 v[8:11], v7
	ds_read_b128 v[12:15], v7 offset:8192
	ds_read_b128 v[128:131], v96
	ds_read_b128 v[132:135], v96 offset:8192
	s_add_i32 s80, s14, 0x8000
	s_and_b32 s80, s80, 0xc000
	v_lshl_add_u64 v[152:153], s[96:97], 0, v[4:5]
	s_mov_b64 s[16:17], 0x9e82000
	v_lshl_add_u64 v[154:155], v[152:153], 0, s[16:17]
	s_mov_b64 s[16:17], 0x9f42000
	v_lshl_add_u64 v[152:153], v[152:153], 0, s[16:17]
	v_lshl_add_u64 v[156:157], s[96:97], 0, v[2:3]
	s_mov_b64 s[16:17], 0x21a00180
	v_lshl_add_u64 v[158:159], v[156:157], 0, s[16:17]
	s_mov_b64 s[16:17], 0x21c00180
	v_lshl_add_u64 v[156:157], v[156:157], 0, s[16:17]
	s_add_i32 s81, s80, s59
	s_add_i32 s16, s80, s54
	s_setprio 1
	ds_read_b128 v[136:139], v240
	s_waitcnt lgkmcnt(4)
	v_mfma_f32_32x32x16_bf16 v[96:111], v[8:11], v[160:163], 0
	ds_read_b128 v[140:143], v240 offset:8192
	s_waitcnt lgkmcnt(4)
	v_mfma_f32_32x32x16_bf16 v[112:127], v[12:15], v[160:163], 0
	ds_read_b128 v[144:147], v241
	s_waitcnt lgkmcnt(4)
	v_mfma_f32_32x32x16_bf16 v[96:111], v[128:131], v[164:167], v[96:111]
	ds_read_b128 v[148:151], v241 offset:8192
	s_waitcnt lgkmcnt(4)
	v_mfma_f32_32x32x16_bf16 v[112:127], v[132:135], v[164:167], v[112:127]
	s_waitcnt lgkmcnt(3)
	v_mfma_f32_32x32x16_bf16 v[96:111], v[136:139], v[168:171], v[96:111]
	s_waitcnt lgkmcnt(2)
	v_mfma_f32_32x32x16_bf16 v[112:127], v[140:143], v[168:171], v[112:127]
	s_waitcnt lgkmcnt(1)
	v_mfma_f32_32x32x16_bf16 v[96:111], v[144:147], v[172:175], v[96:111]
	s_waitcnt lgkmcnt(0)
	v_mfma_f32_32x32x16_bf16 v[112:127], v[148:151], v[172:175], v[112:127]
	s_add_i32 s80, s14, 0xc000
	s_and_b32 s80, s80, 0xc000
	v_add_u32_e32 v144, s80, v193
	ds_read_b128 v[128:131], v144
	ds_read_b128 v[132:135], v144 offset:4096
	ds_read_b128 v[136:139], v144 offset:8192
	ds_read_b128 v[140:143], v144 offset:12288
	v_add_u32_e32 v145, s80, v204
	ds_read_b128 v[224:227], v145
	ds_read_b128 v[228:231], v145 offset:4096
	ds_read_b128 v[232:235], v145 offset:8192
	ds_read_b128 v[236:239], v145 offset:12288
	s_nop 1
	v_exp_f32_e32 v96, v96
	v_exp_f32_e32 v97, v97
	v_exp_f32_e32 v98, v98
	v_exp_f32_e32 v99, v99
	v_exp_f32_e32 v100, v100
	v_exp_f32_e32 v101, v101
	v_exp_f32_e32 v102, v102
	v_exp_f32_e32 v103, v103
	s_waitcnt lgkmcnt(7)
	v_mfma_f32_32x32x16_bf16 v[80:95], v[128:131], v[208:211], v[80:95]
	v_exp_f32_e32 v104, v104
	v_exp_f32_e32 v105, v105
	v_add_f32_e32 v7, v207, v96
	v_add_f32_e32 v7, v97, v7
	s_waitcnt lgkmcnt(6)
	v_mfma_f32_32x32x16_bf16 v[64:79], v[132:135], v[208:211], v[64:79]
	v_exp_f32_e32 v106, v106
	v_exp_f32_e32 v107, v107
	v_add_f32_e32 v7, v98, v7
	v_add_f32_e32 v7, v99, v7
	s_waitcnt lgkmcnt(5)
	v_mfma_f32_32x32x16_bf16 v[48:63], v[136:139], v[208:211], v[48:63]
	v_exp_f32_e32 v108, v108
	v_exp_f32_e32 v109, v109
	v_add_f32_e32 v7, v100, v7
	v_add_f32_e32 v7, v101, v7
	s_waitcnt lgkmcnt(4)
	v_mfma_f32_32x32x16_bf16 v[32:47], v[140:143], v[208:211], v[32:47]
	v_exp_f32_e32 v110, v110
	v_exp_f32_e32 v111, v111
	v_add_f32_e32 v7, v102, v7
	v_add_f32_e32 v7, v103, v7
	s_mov_b32 m0, s81
	s_nop 0
	global_load_lds_dwordx4 v[154:155], off
	v_add_u32_e32 v144, s80, v205
	ds_read_b128 v[128:131], v144
	ds_read_b128 v[132:135], v144 offset:4096
	ds_read_b128 v[136:139], v144 offset:8192
	ds_read_b128 v[140:143], v144 offset:12288
	s_waitcnt lgkmcnt(7)
	v_mfma_f32_32x32x16_bf16 v[80:95], v[224:227], v[212:215], v[80:95]
	v_cvt_pk_bf16_f32 v208, v96, v97
	v_cvt_pk_bf16_f32 v209, v98, v99
	v_exp_f32_e32 v112, v112
	v_exp_f32_e32 v113, v113
	v_add_f32_e32 v7, v104, v7
	s_waitcnt lgkmcnt(6)
	v_mfma_f32_32x32x16_bf16 v[64:79], v[228:231], v[212:215], v[64:79]
	v_cvt_pk_bf16_f32 v210, v100, v101
	v_cvt_pk_bf16_f32 v211, v102, v103
	v_exp_f32_e32 v114, v114
	v_exp_f32_e32 v115, v115
	v_add_f32_e32 v7, v105, v7
	s_waitcnt lgkmcnt(5)
	v_mfma_f32_32x32x16_bf16 v[48:63], v[232:235], v[212:215], v[48:63]
	v_exp_f32_e32 v116, v116
	v_exp_f32_e32 v117, v117
	v_add_f32_e32 v7, v106, v7
	v_add_f32_e32 v7, v107, v7
	v_add_f32_e32 v7, v108, v7
	s_waitcnt lgkmcnt(4)
	v_mfma_f32_32x32x16_bf16 v[32:47], v[236:239], v[212:215], v[32:47]
	v_exp_f32_e32 v118, v118
	v_exp_f32_e32 v119, v119
	v_add_f32_e32 v7, v109, v7
	v_add_f32_e32 v7, v110, v7
	v_add_f32_e32 v7, v111, v7
	s_add_i32 m0, s81, 0x2000
	s_nop 0
	global_load_lds_dwordx4 v[152:153], off
	v_add_u32_e32 v145, s80, v206
	ds_read_b128 v[224:227], v145
	ds_read_b128 v[228:231], v145 offset:4096
	ds_read_b128 v[232:235], v145 offset:8192
	ds_read_b128 v[236:239], v145 offset:12288
	s_waitcnt lgkmcnt(7)
	v_mfma_f32_32x32x16_bf16 v[80:95], v[128:131], v[216:219], v[80:95]
	v_cvt_pk_bf16_f32 v212, v104, v105
	v_cvt_pk_bf16_f32 v213, v106, v107
	v_exp_f32_e32 v120, v120
	v_exp_f32_e32 v121, v121
	v_add_f32_e32 v7, v112, v7
	s_waitcnt lgkmcnt(6)
	v_mfma_f32_32x32x16_bf16 v[64:79], v[132:135], v[216:219], v[64:79]
	v_cvt_pk_bf16_f32 v214, v108, v109
	v_cvt_pk_bf16_f32 v215, v110, v111
	v_exp_f32_e32 v122, v122
	v_exp_f32_e32 v123, v123
	v_add_f32_e32 v7, v113, v7
	s_waitcnt lgkmcnt(5)
	v_mfma_f32_32x32x16_bf16 v[48:63], v[136:139], v[216:219], v[48:63]
	v_exp_f32_e32 v124, v124
	v_exp_f32_e32 v125, v125
	v_add_f32_e32 v7, v114, v7
	v_add_f32_e32 v7, v115, v7
	v_add_f32_e32 v7, v116, v7
	s_waitcnt lgkmcnt(4)
	v_mfma_f32_32x32x16_bf16 v[32:47], v[140:143], v[216:219], v[32:47]
	v_exp_f32_e32 v126, v126
	v_exp_f32_e32 v127, v127
	v_add_f32_e32 v7, v117, v7
	v_add_f32_e32 v7, v118, v7
	v_add_f32_e32 v7, v119, v7
	s_mov_b32 m0, s16
	s_nop 0
	global_load_lds_dwordx4 v[158:159], off
	s_waitcnt lgkmcnt(3)
	v_mfma_f32_32x32x16_bf16 v[80:95], v[224:227], v[220:223], v[80:95]
	v_cvt_pk_bf16_f32 v216, v112, v113
	v_cvt_pk_bf16_f32 v217, v114, v115
	v_cvt_pk_bf16_f32 v218, v116, v117
	v_cvt_pk_bf16_f32 v219, v118, v119
	s_waitcnt lgkmcnt(2)
	v_mfma_f32_32x32x16_bf16 v[64:79], v[228:231], v[220:223], v[64:79]
	v_add_f32_e32 v7, v120, v7
	v_add_f32_e32 v7, v121, v7
	v_add_f32_e32 v7, v122, v7
	v_add_f32_e32 v7, v123, v7
	s_waitcnt lgkmcnt(1)
	v_mfma_f32_32x32x16_bf16 v[48:63], v[232:235], v[220:223], v[48:63]
	v_add_f32_e32 v7, v124, v7
	v_add_f32_e32 v7, v125, v7
	v_add_f32_e32 v7, v126, v7
	v_add_f32_e32 v7, v127, v7
	s_waitcnt lgkmcnt(0)
	v_mfma_f32_32x32x16_bf16 v[32:47], v[236:239], v[220:223], v[32:47]
	s_add_i32 m0, s16, 0x2000
	s_nop 0
	global_load_lds_dwordx4 v[156:157], off
	v_cvt_pk_bf16_f32 v220, v120, v121
	v_cvt_pk_bf16_f32 v221, v122, v123
	v_cvt_pk_bf16_f32 v222, v124, v125
	v_cvt_pk_bf16_f32 v223, v126, v127
	s_setprio 0
	s_branch .LBB1_298
